# norm loop H stores widened: lane pairs merged via DPP, even lanes store dwordx4 (same bytes and addresses)
# baseline (speedup 1.0000x reference)
; DI void ph_norm(const Params& p, int l, int bid, int nb) {
;     ...
;   for (int it = bid; it < ROWS / 8; it += nb) {
;     float4 v[2][4];
;     const float* mod[2];
; #pragma unroll
;     for (int rr = 0; rr < 2; ++rr) {
;       const int row = it * 8 + rr * 4 + w;
;       const int b = row / NTOK, t = row % NTOK;
;       const float* src = xsrc_row(p, l, b, t);
;       mod[rr] = MOD + ((size_t)l * 9 + (t < NCTX ? 8 : b)) * 3072;
; #pragma unroll
;       for (int i = 0; i < 4; ++i) v[rr][i] = *(const float4*)(src + (i * 64 + lane) * 4);
;     }
; #pragma unroll
;     for (int rr = 0; rr < 2; ++rr) {
;       const int row = it * 8 + rr * 4 + w;
;       float ss = 0.f;
; #pragma unroll
;       for (int i = 0; i < 4; ++i) ss += v[rr][i].x * v[rr][i].x + v[rr][i].y * v[rr][i].y + v[rr][i].z * v[rr][i].z + v[rr][i].w * v[rr][i].w;
;       ss = wave_sum(ss);
;       const float rstd = rsqrtf(ss * (1.f / DM) + EPS);
.LBB0_115:
	s_or_b64 exec, exec, s[8:9]
	v_lshlrev_b64 v[8:9], v16, v[8:9]
	v_lshl_add_u64 v[8:9], v[18:19], 0, v[8:9]
	v_lshlrev_b64 v[10:11], 12, v[10:11]
	v_lshl_add_u64 v[8:9], v[8:9], 0, v[10:11]
	v_lshl_add_u64 v[8:9], v[8:9], 0, v[46:47]
	global_load_dwordx4 v[28:31], v[8:9], off
	global_load_dwordx4 v[20:23], v[8:9], off offset:1024
	global_load_dwordx4 v[16:19], v[8:9], off offset:2048
	s_nop 0
	global_load_dwordx4 v[8:11], v[8:9], off offset:3072
	v_add_u32_e32 v45, s2, v58
	s_waitcnt vmcnt(0) lgkmcnt(0)
	v_mov_b32_e32 v70, v25
	v_mov_b32_e32 v71, v13
	v_mov_b32_e32 v58, v24
	v_mov_b32_e32 v59, v12
	v_mov_b32_e32 v78, v5
	v_mov_b32_e32 v79, v1
	v_mul_hi_i32_i24_e32 v85, 0x3000, v45
	v_mul_i32_i24_e32 v84, 0x3000, v45
	v_pk_mul_f32 v[70:71], v[70:71], v[70:71]
	v_mov_b32_e32 v72, v26
	v_mov_b32_e32 v73, v14
	v_mov_b32_e32 v76, v4
	v_mov_b32_e32 v77, v0
	v_pk_mul_f32 v[78:79], v[78:79], v[78:79]
	v_lshl_add_u64 v[84:85], s[0:1], 0, v[84:85]
	v_pk_fma_f32 v[58:59], v[58:59], v[58:59], v[70:71]
	s_mov_b64 s[12:13], 0x1000
	v_mov_b32_e32 v74, v27
	v_mov_b32_e32 v75, v15
	v_mov_b32_e32 v80, v6
	v_mov_b32_e32 v81, v2
	v_pk_fma_f32 v[70:71], v[76:77], v[76:77], v[78:79]
	v_pk_fma_f32 v[58:59], v[72:73], v[72:73], v[58:59]
	v_lshl_add_u64 v[78:79], v[84:85], 0, s[12:13]
	v_mov_b32_e32 v82, v7
	v_mov_b32_e32 v83, v3
	v_pk_fma_f32 v[70:71], v[80:81], v[80:81], v[70:71]
	v_lshl_add_u64 v[80:81], v[84:85], 0, v[46:47]
	v_pk_fma_f32 v[58:59], v[74:75], v[74:75], v[58:59]
	v_lshl_add_u64 v[74:75], v[78:79], 0, v[46:47]
	v_mov_b64_e32 v[66:67], v[104:105]
	v_mov_b64_e32 v[68:69], v[106:107]
	v_pk_fma_f32 v[82:83], v[82:83], v[82:83], v[70:71]
	global_load_dwordx4 v[70:73], v[80:81], off
	global_load_dwordx4 v[120:123], v[80:81], off offset:1024
	global_load_dwordx4 v[124:127], v[80:81], off offset:2048
	global_load_dwordx4 v[128:131], v[80:81], off offset:3072
	s_nop 0
	global_load_dwordx4 v[132:135], v[74:75], off offset:1024
	global_load_dwordx4 v[136:139], v[74:75], off offset:2048
	global_load_dwordx4 v[140:143], v[74:75], off offset:3072
	global_load_dwordx4 v[74:77], v[74:75], off
	v_mov_b32_e32 v85, v58
	v_mov_b32_e32 v87, v82
	s_mov_b32 s8, 0x3a800000
	v_ashrrev_i32_e32 v45, 31, v44
	s_add_i32 s10, s10, s54
	s_mov_b32 s38, 0x800000
	s_cmpk_lt_i32 s10, 0x900
	v_mov_b32_e32 v94, v29
	v_mov_b32_e32 v95, v21
	v_mov_b32_e32 v92, v28
	v_mov_b32_e32 v93, v20
	v_mov_b32_e32 v102, v17
	v_mov_b32_e32 v103, v9
	v_pk_mul_f32 v[94:95], v[94:95], v[94:95]
	v_mov_b32_e32 v88, v30
	v_mov_b32_e32 v89, v22
	v_mov_b32_e32 v100, v16
	v_mov_b32_e32 v101, v8
	v_pk_mul_f32 v[102:103], v[102:103], v[102:103]
	v_pk_fma_f32 v[92:93], v[92:93], v[92:93], v[94:95]
	v_mov_b32_e32 v90, v31
	v_mov_b32_e32 v91, v23
	v_mov_b32_e32 v96, v18
	v_mov_b32_e32 v97, v10
	v_pk_fma_f32 v[94:95], v[100:101], v[100:101], v[102:103]
	v_pk_fma_f32 v[88:89], v[88:89], v[88:89], v[92:93]
	v_mov_b32_e32 v98, v19
	v_mov_b32_e32 v99, v11
	v_pk_fma_f32 v[92:93], v[96:97], v[96:97], v[94:95]
	v_pk_fma_f32 v[88:89], v[90:91], v[90:91], v[88:89]
	v_pk_fma_f32 v[90:91], v[98:99], v[98:99], v[92:93]
	v_mov_b32_e32 v84, v88
	v_mov_b32_e32 v58, v89
	v_mov_b32_e32 v86, v90
	v_pk_add_f32 v[58:59], v[84:85], v[58:59]
	v_mov_b32_e32 v82, v91
	v_pk_add_f32 v[58:59], v[58:59], v[86:87]
	v_lshl_add_u64 v[84:85], v[44:45], 0, v[36:37]
	v_pk_add_f32 v[58:59], v[58:59], v[82:83]
	v_mov_b32_e32 v82, v58
	v_mov_b32_e32 v83, v59
	v_lshlrev_b64 v[84:85], 6, v[84:85]
	v_lshl_add_u64 v[84:85], v[32:33], 0, v[84:85]
	v_permlane32_swap_b32_e32 v82, v58
	v_permlane32_swap_b32_e32 v83, v59
	v_pk_add_f32 v[58:59], v[58:59], v[82:83]
	v_mov_b32_e32 v82, v58
	v_mov_b32_e32 v83, v59
	s_nop 1
	v_permlane16_swap_b32_e32 v82, v58
	v_permlane16_swap_b32_e32 v83, v59
	v_pk_add_f32 v[58:59], v[58:59], v[82:83]
	s_nop 1
	v_add_f32_dpp v58, v58, v58 row_ror:8 row_mask:0xf bank_mask:0xf
	v_add_f32_dpp v59, v59, v59 row_ror:8 row_mask:0xf bank_mask:0xf
	s_nop 0
	v_add_f32_dpp v82, v58, v58 row_shl:4 row_mask:0xf bank_mask:0x5
	v_add_f32_dpp v83, v59, v59 row_shl:4 row_mask:0xf bank_mask:0x5
	v_add_f32_dpp v82, v58, v58 row_shr:4 row_mask:0xf bank_mask:0xa
	v_add_f32_dpp v83, v59, v59 row_shr:4 row_mask:0xf bank_mask:0xa
	s_nop 0
	v_add_f32_dpp v58, v82, v82 quad_perm:[2,3,0,1] row_mask:0xf bank_mask:0xf
	v_add_f32_dpp v59, v83, v83 quad_perm:[2,3,0,1] row_mask:0xf bank_mask:0xf
	s_nop 0
	v_add_f32_dpp v58, v58, v58 quad_perm:[1,0,3,2] row_mask:0xf bank_mask:0xf
	v_add_f32_dpp v59, v59, v59 quad_perm:[1,0,3,2] row_mask:0xf bank_mask:0xf
	s_waitcnt vmcnt(0)
; DI size_t kblk(int row, int col, int nrows) { return ((size_t)(col >> 5) * nrows + row) * 32 + (col & 31); }
; DI unsigned pk2(float a, float b) { hwf32x2 f = {a, b}; hwbf16x2 r = __builtin_convertvector(f, hwbf16x2); return __builtin_bit_cast(unsigned, r); }
; DI void ph_norm(const Params& p, int l, int bid, int nb) {
;     ...
;       for (int i = 0; i < 4; ++i) {
;         const int j = (i * 64 + lane) * 4;
;         const float4 gg = *(const float4*)(g + j);
;         const float4 sh = *(const float4*)(mod[rr] + j);
;         const float4 sc = *(const float4*)(mod[rr] + 1024 + j);
;         uint2 o;
;         o.x = pk2(v[rr][i].x * rstd * gg.x * (1.f + sc.x) + sh.x, v[rr][i].y * rstd * gg.y * (1.f + sc.y) + sh.y);
;         o.y = pk2(v[rr][i].z * rstd * gg.z * (1.f + sc.z) + sh.z, v[rr][i].w * rstd * gg.w * (1.f + sc.w) + sh.w);
;         *(uint2*)(H + kblk(row, j, ROWS)) = o;
	v_pk_add_f32 v[74:75], v[74:75], 1.0 op_sel_hi:[1,0]
	v_pk_add_f32 v[76:77], v[76:77], 1.0 op_sel_hi:[1,0]
	s_nop 0
	v_pk_fma_f32 v[58:59], v[58:59], s[8:9], v[162:163] op_sel_hi:[1,0,0]
	s_mov_b32 s8, 0x800000
	v_mul_f32_e32 v55, 0x4b800000, v59
	v_cmp_gt_f32_e32 vcc, s8, v59
	v_lshl_add_u64 v[82:83], v[78:79], 0, v[48:49]
	s_nop 0
	v_cndmask_b32_e32 v55, v59, v55, vcc
	v_rsq_f32_e32 v55, v55
	s_nop 0
	v_mul_f32_e32 v57, 0x45800000, v55
	v_cndmask_b32_e32 v86, v55, v57, vcc
	v_pk_mul_f32 v[24:25], v[24:25], v[86:87] op_sel_hi:[1,0]
	v_pk_mul_f32 v[26:27], v[26:27], v[86:87] op_sel_hi:[1,0]
	v_pk_mul_f32 v[24:25], v[66:67], v[24:25]
	v_pk_mul_f32 v[26:27], v[68:69], v[26:27]
	v_pk_fma_f32 v[24:25], v[74:75], v[24:25], v[70:71]
	v_pk_fma_f32 v[26:27], v[26:27], v[76:77], v[72:73]
	v_cvt_pk_bf16_f32 v24, v24, v25
	v_cvt_pk_bf16_f32 v25, v26, v27
	s_nop 1
	v_mov_b32_dpp v26, v24 quad_perm:[1,1,3,3] row_mask:0xf bank_mask:0xf
	v_mov_b32_dpp v27, v25 quad_perm:[1,1,3,3] row_mask:0xf bank_mask:0xf
	s_mov_b32 exec_lo, 0x55555555
	s_mov_b32 exec_hi, 0x55555555
	global_store_dwordx4 v[84:85], v[24:27], off
	s_mov_b64 exec, -1
	s_nop 0
	v_mov_b64_e32 v[24:25], v[108:109]
	v_mov_b64_e32 v[26:27], v[110:111]
	s_nop 0
	v_mov_b64_e32 v[66:67], v[132:133]
	v_mov_b64_e32 v[68:69], v[134:135]
	v_mov_b64_e32 v[70:71], v[120:121]
	v_mov_b64_e32 v[72:73], v[122:123]
	v_pk_mul_f32 v[12:13], v[12:13], v[86:87] op_sel_hi:[1,0]
	v_pk_mul_f32 v[14:15], v[14:15], v[86:87] op_sel_hi:[1,0]
	v_lshl_add_u64 v[74:75], v[44:45], 0, v[38:39]
	v_lshlrev_b64 v[74:75], 6, v[74:75]
	v_lshl_add_u64 v[74:75], v[32:33], 0, v[74:75]
	v_lshl_add_u64 v[76:77], v[78:79], 0, v[50:51]
	v_pk_mul_f32 v[4:5], v[4:5], v[86:87] op_sel_hi:[1,0]
	v_pk_mul_f32 v[6:7], v[6:7], v[86:87] op_sel_hi:[1,0]
	v_pk_mul_f32 v[0:1], v[0:1], v[86:87] op_sel_hi:[1,0]
	v_pk_mul_f32 v[2:3], v[2:3], v[86:87] op_sel_hi:[1,0]
	v_add_u32_e32 v55, s2, v56
	v_mul_hi_i32_i24_e32 v57, 0x3000, v55
	v_mul_i32_i24_e32 v56, 0x3000, v55
	v_lshl_add_u64 v[56:57], s[0:1], 0, v[56:57]
	v_cmp_gt_f32_e32 vcc, s8, v58
	v_ashrrev_i32_e32 v55, 31, v54
	v_readlane_b32 s8, v254, 11
	v_pk_mul_f32 v[12:13], v[12:13], v[24:25]
	s_waitcnt lgkmcnt(0)
	v_pk_add_f32 v[24:25], v[66:67], 1.0 op_sel_hi:[1,0]
	v_pk_mul_f32 v[14:15], v[14:15], v[26:27]
	v_pk_add_f32 v[26:27], v[68:69], 1.0 op_sel_hi:[1,0]
	v_pk_fma_f32 v[12:13], v[12:13], v[24:25], v[70:71]
	v_pk_fma_f32 v[14:15], v[14:15], v[26:27], v[72:73]
	v_cvt_pk_bf16_f32 v12, v12, v13
	v_cvt_pk_bf16_f32 v13, v14, v15
	s_nop 1
	v_mov_b32_dpp v14, v12 quad_perm:[1,1,3,3] row_mask:0xf bank_mask:0xf
	v_mov_b32_dpp v15, v13 quad_perm:[1,1,3,3] row_mask:0xf bank_mask:0xf
	s_mov_b32 exec_lo, 0x55555555
	s_mov_b32 exec_hi, 0x55555555
	global_store_dwordx4 v[74:75], v[12:15], off
	s_mov_b64 exec, -1
	s_nop 0
	v_mov_b64_e32 v[12:13], v[112:113]
	v_mov_b64_e32 v[14:15], v[114:115]
	s_nop 0
	v_mov_b64_e32 v[24:25], v[136:137]
	v_mov_b64_e32 v[26:27], v[138:139]
	v_mov_b64_e32 v[66:67], v[124:125]
	v_mov_b64_e32 v[68:69], v[126:127]
	v_lshl_add_u64 v[70:71], v[44:45], 0, v[40:41]
	v_lshlrev_b64 v[70:71], 6, v[70:71]
	v_lshl_add_u64 v[70:71], v[32:33], 0, v[70:71]
	v_lshl_add_u64 v[72:73], v[78:79], 0, v[52:53]
	v_pk_mul_f32 v[4:5], v[4:5], v[12:13]
	s_waitcnt lgkmcnt(0)
	v_pk_add_f32 v[12:13], v[24:25], 1.0 op_sel_hi:[1,0]
	v_pk_mul_f32 v[6:7], v[6:7], v[14:15]
	v_pk_add_f32 v[14:15], v[26:27], 1.0 op_sel_hi:[1,0]
	v_pk_fma_f32 v[4:5], v[4:5], v[12:13], v[66:67]
	v_pk_fma_f32 v[6:7], v[6:7], v[14:15], v[68:69]
	v_cvt_pk_bf16_f32 v4, v4, v5
	v_cvt_pk_bf16_f32 v5, v6, v7
	s_nop 1
	v_mov_b32_dpp v6, v4 quad_perm:[1,1,3,3] row_mask:0xf bank_mask:0xf
	v_mov_b32_dpp v7, v5 quad_perm:[1,1,3,3] row_mask:0xf bank_mask:0xf
	s_mov_b32 exec_lo, 0x55555555
	s_mov_b32 exec_hi, 0x55555555
	global_store_dwordx4 v[70:71], v[4:7], off
	s_mov_b64 exec, -1
	s_nop 0
	v_mov_b64_e32 v[4:5], v[116:117]
	v_mov_b64_e32 v[6:7], v[118:119]
	s_nop 0
	v_mov_b64_e32 v[12:13], v[140:141]
	v_mov_b64_e32 v[14:15], v[142:143]
	v_mov_b64_e32 v[24:25], v[128:129]
	v_mov_b64_e32 v[26:27], v[130:131]
	v_lshl_add_u64 v[66:67], v[44:45], 0, v[42:43]
	v_lshlrev_b64 v[66:67], 6, v[66:67]
	v_lshl_add_u64 v[66:67], v[32:33], 0, v[66:67]
	v_lshl_add_u64 v[68:69], v[56:57], 0, s[12:13]
	v_lshl_add_u64 v[70:71], v[68:69], 0, v[46:47]
	v_mul_f32_e32 v45, 0x4b800000, v58
	v_cndmask_b32_e32 v45, v58, v45, vcc
	v_rsq_f32_e32 v45, v45
	v_add_u32_e32 v44, s8, v44
	v_mul_f32_e32 v58, 0x45800000, v45
	v_cndmask_b32_e32 v58, v45, v58, vcc
	v_pk_mul_f32 v[28:29], v[28:29], v[58:59] op_sel_hi:[1,0]
	v_pk_mul_f32 v[30:31], v[30:31], v[58:59] op_sel_hi:[1,0]
	v_pk_mul_f32 v[20:21], v[20:21], v[58:59] op_sel_hi:[1,0]
	v_pk_mul_f32 v[22:23], v[22:23], v[58:59] op_sel_hi:[1,0]
	v_pk_mul_f32 v[16:17], v[16:17], v[58:59] op_sel_hi:[1,0]
	v_pk_mul_f32 v[18:19], v[18:19], v[58:59] op_sel_hi:[1,0]
	v_pk_mul_f32 v[8:9], v[8:9], v[58:59] op_sel_hi:[1,0]
	v_pk_mul_f32 v[10:11], v[10:11], v[58:59] op_sel_hi:[1,0]
	v_pk_mul_f32 v[0:1], v[0:1], v[4:5]
	s_waitcnt lgkmcnt(0)
; DI size_t kblk(int row, int col, int nrows) { return ((size_t)(col >> 5) * nrows + row) * 32 + (col & 31); }
; DI unsigned pk2(float a, float b) { hwf32x2 f = {a, b}; hwbf16x2 r = __builtin_convertvector(f, hwbf16x2); return __builtin_bit_cast(unsigned, r); }
; DI void ph_norm(const Params& p, int l, int bid, int nb) {
;     ...
;       for (int i = 0; i < 4; ++i) {
;         const int j = (i * 64 + lane) * 4;
;         const float4 gg = *(const float4*)(g + j);
;         const float4 sh = *(const float4*)(mod[rr] + j);
;         const float4 sc = *(const float4*)(mod[rr] + 1024 + j);
;         uint2 o;
;         o.x = pk2(v[rr][i].x * rstd * gg.x * (1.f + sc.x) + sh.x, v[rr][i].y * rstd * gg.y * (1.f + sc.y) + sh.y);
;         o.y = pk2(v[rr][i].z * rstd * gg.z * (1.f + sc.z) + sh.z, v[rr][i].w * rstd * gg.w * (1.f + sc.w) + sh.w);
;         *(uint2*)(H + kblk(row, j, ROWS)) = o;
	v_pk_add_f32 v[4:5], v[12:13], 1.0 op_sel_hi:[1,0]
	v_pk_mul_f32 v[2:3], v[2:3], v[6:7]
	v_pk_add_f32 v[6:7], v[14:15], 1.0 op_sel_hi:[1,0]
	v_pk_fma_f32 v[0:1], v[0:1], v[4:5], v[24:25]
	v_pk_fma_f32 v[2:3], v[2:3], v[6:7], v[26:27]
	v_cvt_pk_bf16_f32 v0, v0, v1
	v_cvt_pk_bf16_f32 v1, v2, v3
	s_nop 1
	v_mov_b32_dpp v2, v0 quad_perm:[1,1,3,3] row_mask:0xf bank_mask:0xf
	v_mov_b32_dpp v3, v1 quad_perm:[1,1,3,3] row_mask:0xf bank_mask:0xf
	s_mov_b32 exec_lo, 0x55555555
	s_mov_b32 exec_hi, 0x55555555
	global_store_dwordx4 v[66:67], v[0:3], off
	s_mov_b64 exec, -1
	s_nop 0
	v_mov_b64_e32 v[0:1], v[104:105]
	v_mov_b64_e32 v[2:3], v[106:107]
	s_nop 0
	global_load_dwordx4 v[4:7], v[70:71], off
	global_load_dwordx4 v[144:147], v[70:71], off offset:1024
	global_load_dwordx4 v[148:151], v[70:71], off offset:2048
	global_load_dwordx4 v[152:155], v[70:71], off offset:3072
	v_lshl_add_u64 v[24:25], v[56:57], 0, v[46:47]
	global_load_dwordx4 v[12:15], v[24:25], off
	global_load_dwordx4 v[156:159], v[24:25], off offset:1024
	global_load_dwordx4 v[196:199], v[24:25], off offset:2048
	global_load_dwordx4 v[200:203], v[24:25], off offset:3072
	v_lshl_add_u64 v[26:27], v[54:55], 0, v[36:37]
	v_lshlrev_b64 v[26:27], 6, v[26:27]
	v_lshl_add_u64 v[26:27], v[32:33], 0, v[26:27]
	v_lshl_add_u64 v[56:57], v[68:69], 0, v[48:49]
	s_waitcnt vmcnt(0)
	v_pk_mul_f32 v[0:1], v[0:1], v[28:29]
	s_waitcnt lgkmcnt(0)
	v_pk_add_f32 v[4:5], v[4:5], 1.0 op_sel_hi:[1,0]
	v_pk_mul_f32 v[2:3], v[2:3], v[30:31]
	v_pk_add_f32 v[6:7], v[6:7], 1.0 op_sel_hi:[1,0]
	v_pk_fma_f32 v[0:1], v[4:5], v[0:1], v[12:13]
	v_pk_fma_f32 v[2:3], v[2:3], v[6:7], v[14:15]
	v_cvt_pk_bf16_f32 v0, v0, v1
	v_cvt_pk_bf16_f32 v1, v2, v3
	s_nop 1
	v_mov_b32_dpp v2, v0 quad_perm:[1,1,3,3] row_mask:0xf bank_mask:0xf
	v_mov_b32_dpp v3, v1 quad_perm:[1,1,3,3] row_mask:0xf bank_mask:0xf
	s_mov_b32 exec_lo, 0x55555555
	s_mov_b32 exec_hi, 0x55555555
	global_store_dwordx4 v[26:27], v[0:3], off
	s_mov_b64 exec, -1
	s_nop 0
	v_mov_b64_e32 v[0:1], v[108:109]
	v_mov_b64_e32 v[2:3], v[110:111]
	s_nop 0
	v_mov_b64_e32 v[4:5], v[144:145]
	v_mov_b64_e32 v[6:7], v[146:147]
	v_mov_b64_e32 v[12:13], v[156:157]
	v_mov_b64_e32 v[14:15], v[158:159]
	v_lshl_add_u64 v[26:27], v[54:55], 0, v[38:39]
	v_lshlrev_b64 v[26:27], 6, v[26:27]
	v_lshl_add_u64 v[26:27], v[32:33], 0, v[26:27]
	v_lshl_add_u64 v[28:29], v[68:69], 0, v[50:51]
	v_pk_mul_f32 v[0:1], v[20:21], v[0:1]
	s_waitcnt lgkmcnt(0)
	v_pk_add_f32 v[4:5], v[4:5], 1.0 op_sel_hi:[1,0]
	v_pk_mul_f32 v[2:3], v[22:23], v[2:3]
	v_pk_add_f32 v[6:7], v[6:7], 1.0 op_sel_hi:[1,0]
	v_pk_fma_f32 v[0:1], v[0:1], v[4:5], v[12:13]
	v_pk_fma_f32 v[2:3], v[2:3], v[6:7], v[14:15]
	v_cvt_pk_bf16_f32 v0, v0, v1
	v_cvt_pk_bf16_f32 v1, v2, v3
	s_nop 1
	v_mov_b32_dpp v2, v0 quad_perm:[1,1,3,3] row_mask:0xf bank_mask:0xf
	v_mov_b32_dpp v3, v1 quad_perm:[1,1,3,3] row_mask:0xf bank_mask:0xf
	s_mov_b32 exec_lo, 0x55555555
	s_mov_b32 exec_hi, 0x55555555
	global_store_dwordx4 v[26:27], v[0:3], off
	s_mov_b64 exec, -1
	s_nop 0
	v_mov_b64_e32 v[0:1], v[112:113]
	v_mov_b64_e32 v[2:3], v[114:115]
	s_nop 0
	v_mov_b64_e32 v[4:5], v[148:149]
	v_mov_b64_e32 v[6:7], v[150:151]
	v_mov_b64_e32 v[12:13], v[196:197]
	v_mov_b64_e32 v[14:15], v[198:199]
	v_lshl_add_u64 v[20:21], v[54:55], 0, v[40:41]
	v_lshlrev_b64 v[20:21], 6, v[20:21]
	v_lshl_add_u64 v[20:21], v[32:33], 0, v[20:21]
	v_lshl_add_u64 v[22:23], v[68:69], 0, v[52:53]
	v_pk_mul_f32 v[0:1], v[16:17], v[0:1]
	s_waitcnt lgkmcnt(0)
	v_pk_add_f32 v[4:5], v[4:5], 1.0 op_sel_hi:[1,0]
	v_pk_mul_f32 v[2:3], v[18:19], v[2:3]
	v_pk_add_f32 v[6:7], v[6:7], 1.0 op_sel_hi:[1,0]
	v_pk_fma_f32 v[0:1], v[0:1], v[4:5], v[12:13]
	v_pk_fma_f32 v[2:3], v[2:3], v[6:7], v[14:15]
	v_cvt_pk_bf16_f32 v0, v0, v1
	v_cvt_pk_bf16_f32 v1, v2, v3
	s_nop 1
	v_mov_b32_dpp v2, v0 quad_perm:[1,1,3,3] row_mask:0xf bank_mask:0xf
	v_mov_b32_dpp v3, v1 quad_perm:[1,1,3,3] row_mask:0xf bank_mask:0xf
	s_mov_b32 exec_lo, 0x55555555
	s_mov_b32 exec_hi, 0x55555555
	global_store_dwordx4 v[20:21], v[0:3], off
	s_mov_b64 exec, -1
	s_nop 0
	v_mov_b64_e32 v[0:1], v[116:117]
	v_mov_b64_e32 v[2:3], v[118:119]
	s_nop 0
	v_mov_b64_e32 v[4:5], v[152:153]
	v_mov_b64_e32 v[6:7], v[154:155]
	v_mov_b64_e32 v[12:13], v[200:201]
	v_mov_b64_e32 v[14:15], v[202:203]
	v_lshl_add_u64 v[16:17], v[54:55], 0, v[42:43]
	v_lshlrev_b64 v[16:17], 6, v[16:17]
	v_lshl_add_u64 v[16:17], v[32:33], 0, v[16:17]
	v_pk_mul_f32 v[0:1], v[8:9], v[0:1]
	s_waitcnt lgkmcnt(0)
	v_pk_add_f32 v[4:5], v[4:5], 1.0 op_sel_hi:[1,0]
	v_pk_mul_f32 v[2:3], v[10:11], v[2:3]
	v_pk_add_f32 v[6:7], v[6:7], 1.0 op_sel_hi:[1,0]
	v_pk_fma_f32 v[0:1], v[0:1], v[4:5], v[12:13]
	v_pk_fma_f32 v[2:3], v[2:3], v[6:7], v[14:15]
	v_cvt_pk_bf16_f32 v0, v0, v1
	v_cvt_pk_bf16_f32 v1, v2, v3
	s_nop 1
	v_mov_b32_dpp v2, v0 quad_perm:[1,1,3,3] row_mask:0xf bank_mask:0xf
	v_mov_b32_dpp v3, v1 quad_perm:[1,1,3,3] row_mask:0xf bank_mask:0xf
	s_mov_b32 exec_lo, 0x55555555
	s_mov_b32 exec_hi, 0x55555555
	global_store_dwordx4 v[16:17], v[0:3], off
	s_mov_b64 exec, -1
	s_nop 0
	s_cbranch_scc0 .LBB0_124
